# token-0 mixers: task->workgroup map permuted so the four memory-head tasks of a batch run on the same XCD (shared memory rows hit L2)
# speedup vs baseline: 1.0112x; 1.0064x over previous
; #define LAS __attribute__((address_space(3)))
; DI float silu_f(float x) { return x / (1.0f + __expf(-x)); }
; DI void tok0_mem(ldsp lds, const float* qm, const float* memb, const float* mnw, const float* Wkv, int hm, LAS float* out64, int tid, int wid, int lane) {
;     LAS float* U = (LAS float*)lds; LAS float* SC = U + 1024; LAS float* RSN = SC + 256; LAS float* MB = RSN + 256; LAS float* QS = MB + 2048; LAS float* PO = QS + 64;
;     if (tid < 64) QS[tid] = qm[tid];
;     __syncthreads();
; DI void tok0_mix_dil(ldsp lds, const Params& p, const float* P, float* BRo, int task, int tid, int wid, int lane) {
;     const int b = task >> 2, hm = task & 3;
;     const float* pr = P + (size_t)b * 8192;
;     LAS float* OUT = (LAS float*)(lds + 65536); LAS float* S18 = OUT + 64;
;     tok0_mem(lds, pr + DB_QM + hm * 64, p.mem + (size_t)b * 256 * 1024, p.mem_norm_w, p.w_memkv + (size_t)1024 * 512, hm, OUT, tid, wid, lane);
;     if (tid < 64) BRo[(size_t)b * 1024 + 768 + hm * 64 + tid] = OUT[tid] * silu_f(pr[DB_GATE + 768 + hm * 64 + tid]);
;     if (hm == 0) {
;         for (int pi = wid; pi < 18; pi += 8) {
;             const int g = pi / 6, head = pi - g * 6;
;             const float* qp = pr + g * 2304 + head * 128; const float* kp = qp + 768;
;             const float t = wave_sum(qp[lane] * kp[lane] + qp[64 + lane] * kp[64 + lane]) * 0.08838834764831845f;
;             if (lane == 0) S18[pi] = t;
;         }
;         __syncthreads();
;         for (int c = tid; c < 768; c += 512) {
.LBB0_91:
	s_andn2_b64 vcc, exec, s[40:41]
	s_cbranch_vccnz .LBB0_126
	v_readlane_b32 s14, v251, 45
	v_readlane_b32 s15, v251, 46
	s_andn2_b64 vcc, exec, s[14:15]
	s_waitcnt vmcnt(0) lgkmcnt(0)
	s_barrier
	s_cbranch_vccnz .LBB0_126
	v_mov_b32_e32 v33, v12
	v_mov_b64_e32 v[30:31], v[32:33]
	v_ashrrev_i32_e32 v33, 31, v32
	v_lshlrev_b64 v[0:1], 11, v[32:33]
	s_mov_b64 s[14:15], 0x100000
	v_lshl_add_u64 v[78:79], v[0:1], 0, s[14:15]
	v_and_b32_e32 v0, 64, v233
	v_add_u32_e32 v0, 64, v0
	v_xor_b32_e32 v1, 32, v233
	v_cmp_lt_i32_e32 vcc, v1, v0
	s_lshl_b32 s22, s16, 5
	v_readlane_b32 s0, v255, 14
	v_cndmask_b32_e32 v1, v233, v1, vcc
	v_lshlrev_b32_e32 v95, 2, v1
	v_xor_b32_e32 v1, 16, v233
	v_cmp_lt_i32_e32 vcc, v1, v0
	s_cmp_lt_u32 s0, 64
	v_lshlrev_b32_e32 v3, 2, v32
	v_cndmask_b32_e32 v1, v233, v1, vcc
	v_lshlrev_b32_e32 v96, 2, v1
	v_xor_b32_e32 v1, 8, v233
	v_cmp_lt_i32_e32 vcc, v1, v0
	v_readlane_b32 s48, v254, 15
	s_cselect_b64 s[46:47], -1, 0
	v_cndmask_b32_e32 v1, v233, v1, vcc
	v_lshlrev_b32_e32 v97, 2, v1
	v_xor_b32_e32 v1, 4, v233
	v_cmp_lt_i32_e32 vcc, v1, v0
	s_add_i32 s0, 0, 0x10000
	v_readlane_b32 s49, v254, 16
	v_cndmask_b32_e32 v1, v233, v1, vcc
	v_lshlrev_b32_e32 v98, 2, v1
	v_xor_b32_e32 v1, 2, v233
	v_cmp_lt_i32_e32 vcc, v1, v0
	v_add_u32_e32 v102, s0, v3
	s_cmp_lt_i32 s16, 18
	v_cndmask_b32_e32 v1, v233, v1, vcc
	v_lshlrev_b32_e32 v99, 2, v1
	v_xor_b32_e32 v1, 1, v233
	v_cmp_lt_i32_e32 vcc, v1, v0
	s_movk_i32 s0, 0x300
	v_lshlrev_b32_e32 v4, 4, v32
	v_cndmask_b32_e32 v0, v233, v1, vcc
	v_ashrrev_i32_e32 v1, 8, v32
	v_lshlrev_b32_e32 v100, 2, v0
	v_lshlrev_b32_e32 v0, 7, v1
	s_cselect_b64 s[48:49], -1, 0
	v_cmp_gt_i32_e64 s[42:43], s0, v32
	s_add_i32 s0, 0, 0x1000
	v_lshlrev_b32_e32 v2, 12, v1
	v_and_b32_e32 v4, 0xff0, v4
	v_ashrrev_i32_e32 v7, 4, v32
	s_lshl_b32 s14, s16, 7
	s_ashr_i32 s23, s22, 31
	v_lshl_add_u32 v104, v1, 9, s0
	v_ashrrev_i32_e32 v1, 31, v0
	v_add_u32_e32 v13, 0, v3
	v_add3_u32 v101, 0, v2, v4
	v_lshlrev_b32_e32 v2, 5, v7
	s_add_i32 s15, s0, s14
	s_lshl_b64 s[22:23], s[22:23], 12
	v_readlane_b32 s17, v254, 14
	v_lshlrev_b64 v[0:1], 12, v[0:1]
	v_and_b32_e32 v3, 0xff, v32
	v_readlane_b32 s50, v254, 17
	v_readlane_b32 s51, v254, 18
	s_add_u32 s22, s17, s22
	v_readlane_b32 s17, v254, 31
	v_lshl_or_b32 v0, v3, 4, v0
	v_ashrrev_i32_e32 v3, 31, v2
	s_addc_u32 s23, s17, s23
	v_lshl_add_u64 v[86:87], s[50:51], 0, v[0:1]
	v_lshlrev_b64 v[0:1], 11, v[2:3]
	s_lshl_b32 s0, s16, 2
	v_lshlrev_b64 v[80:81], 2, v[32:33]
	v_readlane_b32 s52, v254, 19
	v_readlane_b32 s53, v254, 20
	v_readlane_b32 s56, v254, 23
	v_readlane_b32 s57, v254, 24
	v_lshl_add_u32 v94, v238, 4, 0
	v_mul_i32_i24_e32 v6, -12, v238
	v_lshl_add_u32 v8, v7, 8, 0
	v_lshlrev_b32_e32 v9, 4, v155
	v_lshlrev_b32_e32 v4, 4, v238
	v_mov_b32_e32 v5, v12
	v_lshl_or_b32 v0, v155, 4, v0
	s_add_i32 s17, s0, 0
	v_cmp_gt_i32_e64 s[38:39], 64, v32
	v_lshl_add_u64 v[82:83], s[52:53], 0, v[80:81]
	v_cmp_eq_u32_e64 s[40:41], 0, v238
	v_add_u32_e32 v103, 0x1f00, v32
	v_lshl_add_u64 v[84:85], s[22:23], 0, v[4:5]
	v_lshl_add_u64 v[88:89], s[56:57], 0, v[0:1]
	v_lshl_add_u32 v105, v7, 7, 0
	s_add_i32 s17, s17, 0x10100
	v_add_u32_e32 v106, v94, v6
	v_add_u32_e32 v107, v8, v9
	v_lshlrev_b32_e32 v108, 2, v238
	s_and_b32 s34, s78, 7
	s_lshl_b32 s34, s34, 4
	s_lshr_b32 s19, s78, 3
	s_or_b32 s34, s34, s19
	s_cmpk_lt_u32 s78, 0x80
	s_cselect_b32 s34, s34, s78
	s_mov_b32 s19, s34
	v_readlane_b32 s54, v254, 21
	v_readlane_b32 s55, v254, 22
	v_readlane_b32 s58, v254, 25
	v_readlane_b32 s59, v254, 26
	v_readlane_b32 s60, v254, 27
	v_readlane_b32 s61, v254, 28
	v_readlane_b32 s62, v254, 29
	v_readlane_b32 s63, v254, 30
	s_branch .LBB0_96

; #define LAS __attribute__((address_space(3)))
; DI float silu_f(float x) { return x / (1.0f + __expf(-x)); }
; DI void tok0_mem(ldsp lds, const float* qm, const float* memb, const float* mnw, const float* Wkv, int hm, LAS float* out64, int tid, int wid, int lane) {
;     LAS float* U = (LAS float*)lds; LAS float* SC = U + 1024; LAS float* RSN = SC + 256; LAS float* MB = RSN + 256; LAS float* QS = MB + 2048; LAS float* PO = QS + 64;
;     if (tid < 64) QS[tid] = qm[tid];
;     __syncthreads();
; DI void tok0_mix_gla(ldsp lds, const Params& p, const float* P, float* BRo, int task, int tid, int wid, int lane) {
;     const int b = task >> 2, hm = task & 3;
;     const float* pr = P + (size_t)b * 8192;
;     LAS float* OUT = (LAS float*)(lds + 65536); LAS float* R3 = OUT + 64;
;     tok0_mem(lds, pr + GA_QM + hm * 64, p.mem + (size_t)b * 256 * 1024, p.mem_norm_w, p.w_memkv, hm, OUT, tid, wid, lane);
;     if (tid < 64) BRo[(size_t)b * 1024 + 768 + hm * 64 + tid] = OUT[tid] * silu_f(pr[GA_GATE + 768 + hm * 64 + tid]);
;     const float* qp = pr + hm * 96; const float* kp = pr + GA_K + hm * 96;
;     const float a = wave_sum(qp[lane] * kp[lane] + (lane < 32 ? qp[64 + lane] * kp[64 + lane] : 0.f)) * 0.10206207261596575f;
;     float ve = 0.f;
;     if (tid < 192) ve = pr[GA_V + hm * 192 + tid];
;     const float sq = wave_sum(ve * ve);
;     if (lane == 0 && wid < 3) R3[wid] = sq;
;     __syncthreads();
;     const float msv = (R3[0] + R3[1] + R3[2]) * (1.0f / 192.0f);
;     const float rs = rsqrtf(a * a * msv + 1e-6f);
;     if (tid < 192) BRo[(size_t)b * 1024 + hm * 192 + tid] = a * ve * rs * p.gla_norm_w[tid] * silu_f(pr[GA_GATE + hm * 192 + tid]);
.LBB0_827:
	v_readlane_b32 s14, v251, 43
	v_readlane_b32 s18, v255, 7
	v_readlane_b32 s15, v251, 44
	v_readlane_b32 s19, v255, 8
	s_or_b64 s[14:15], s[18:19], s[14:15]
	s_and_b64 vcc, exec, s[14:15]
	s_cbranch_vccnz .LBB0_860
	v_and_b32_e32 v2, 64, v233
	v_add_u32_e32 v2, 64, v2
	v_xor_b32_e32 v4, 32, v233
	v_cmp_lt_i32_e32 vcc, v4, v2
	s_lshl_b32 s22, s16, 5
	v_readlane_b32 s0, v255, 14
	v_cndmask_b32_e32 v4, v233, v4, vcc
	v_lshlrev_b32_e32 v97, 2, v4
	v_xor_b32_e32 v4, 16, v233
	v_cmp_lt_i32_e32 vcc, v4, v2
	v_lshlrev_b64 v[0:1], 11, v[32:33]
	s_mov_b64 s[14:15], 0x100000
	v_cndmask_b32_e32 v4, v233, v4, vcc
	v_lshlrev_b32_e32 v98, 2, v4
	v_xor_b32_e32 v4, 8, v233
	v_cmp_lt_i32_e32 vcc, v4, v2
	s_cmp_lt_u32 s0, 64
	v_lshlrev_b32_e32 v3, 2, v32
	v_cndmask_b32_e32 v4, v233, v4, vcc
	v_lshlrev_b32_e32 v99, 2, v4
	v_xor_b32_e32 v4, 4, v233
	v_cmp_lt_i32_e32 vcc, v4, v2
	v_lshl_add_u64 v[78:79], v[0:1], 0, s[14:15]
	v_readlane_b32 s44, v254, 15
	v_cndmask_b32_e32 v4, v233, v4, vcc
	v_lshlrev_b32_e32 v100, 2, v4
	v_xor_b32_e32 v4, 2, v233
	v_cmp_lt_i32_e32 vcc, v4, v2
	s_cselect_b64 s[14:15], -1, 0
	s_add_i32 s0, 0, 0x10000
	v_readlane_b32 s45, v254, 16
	v_cndmask_b32_e32 v4, v233, v4, vcc
	v_add_u32_e32 v104, s0, v3
	s_movk_i32 s0, 0xc0
	s_cmp_lt_i32 s16, 3
	v_lshlrev_b32_e32 v101, 2, v4
	v_xor_b32_e32 v4, 1, v233
	v_cmp_gt_i32_e64 s[44:45], s0, v32
	s_cselect_b64 s[18:19], -1, 0
	s_lshl_b32 s0, s16, 2
	v_readlane_b32 s56, v254, 27
	v_readlane_b32 s57, v254, 28
	v_readlane_b32 s58, v254, 29
	v_readlane_b32 s59, v254, 30
	v_cmp_lt_i32_e32 vcc, v4, v2
	v_cmp_eq_u32_e64 s[40:41], 0, v238
	s_add_i32 s17, s0, 0
	s_lshl_b32 s0, s16, 7
	s_add_i32 s26, 0, 0x1000
	s_ashr_i32 s23, s22, 31
	v_cndmask_b32_e32 v2, v233, v4, vcc
	v_ashrrev_i32_e32 v5, 8, v32
	v_lshlrev_b32_e32 v7, 4, v32
	s_and_b64 s[18:19], s[40:41], s[18:19]
	s_add_i32 s17, s17, 0x10100
	v_readlane_b32 s56, v251, 0
	s_add_i32 s34, s26, s0
	s_lshl_b64 s[22:23], s[22:23], 12
	v_readlane_b32 s0, v254, 14
	v_lshlrev_b64 v[0:1], 2, v[32:33]
	v_readlane_b32 s48, v254, 19
	v_readlane_b32 s49, v254, 20
	v_lshlrev_b32_e32 v102, 2, v2
	v_lshlrev_b32_e32 v2, 7, v5
	v_lshlrev_b32_e32 v4, 12, v5
	v_and_b32_e32 v7, 0xff0, v7
	v_readlane_b32 s58, v251, 2
	v_readlane_b32 s59, v251, 3
	s_add_u32 s22, s0, s22
	v_readlane_b32 s0, v254, 31
	v_add_u32_e32 v13, 0, v3
	v_lshl_add_u64 v[80:81], s[48:49], 0, v[0:1]
	v_add3_u32 v103, 0, v4, v7
	v_ashrrev_i32_e32 v7, 4, v32
	v_lshl_add_u64 v[82:83], s[58:59], 0, v[0:1]
	v_lshlrev_b32_e32 v0, 4, v238
	v_mov_b32_e32 v1, v12
	s_addc_u32 s23, s0, s23
	v_ashrrev_i32_e32 v3, 31, v2
	v_lshlrev_b32_e32 v4, 5, v7
	v_lshl_add_u64 v[84:85], s[22:23], 0, v[0:1]
	v_lshlrev_b64 v[0:1], 12, v[2:3]
	v_and_b32_e32 v2, 0xff, v32
	v_readlane_b32 s46, v254, 17
	v_readlane_b32 s47, v254, 18
	v_lshl_add_u32 v107, v5, 9, s26
	v_lshl_or_b32 v0, v2, 4, v0
	v_ashrrev_i32_e32 v5, 31, v4
	v_lshl_add_u64 v[86:87], s[46:47], 0, v[0:1]
	v_lshlrev_b64 v[0:1], 11, v[4:5]
	v_readlane_b32 s52, v254, 23
	v_readlane_b32 s53, v254, 24
	v_lshl_add_u32 v96, v238, 4, 0
	v_mul_i32_i24_e32 v6, -12, v238
	v_lshl_add_u32 v8, v7, 8, 0
	v_lshlrev_b32_e32 v9, 4, v155
	v_lshl_or_b32 v0, v155, 4, v0
	v_cmp_gt_i32_e64 s[38:39], 64, v32
	v_mov_b32_e32 v30, v32
	v_mov_b32_e32 v31, v12
	v_add_u32_e32 v105, 0xa10, v32
	v_cmp_gt_u32_e64 s[42:43], 32, v238
	v_add_u32_e32 v106, 0x710, v32
	v_lshl_add_u64 v[88:89], s[52:53], 0, v[0:1]
	v_lshl_add_u32 v108, v7, 7, 0
	v_add_u32_e32 v109, v96, v6
	v_add_u32_e32 v110, v8, v9
	v_lshlrev_b32_e32 v90, 2, v238
	s_and_b32 s36, s78, 7
	s_lshl_b32 s36, s36, 4
	s_lshr_b32 s35, s78, 3
	s_or_b32 s36, s36, s35
	s_cmpk_lt_u32 s78, 0x80
	s_cselect_b32 s36, s36, s78
	s_mov_b32 s35, s36
	v_readlane_b32 s50, v254, 21
	v_readlane_b32 s51, v254, 22
	v_readlane_b32 s54, v254, 25
	v_readlane_b32 s55, v254, 26
	v_readlane_b32 s57, v251, 1
	v_readlane_b32 s60, v251, 4
	v_readlane_b32 s61, v251, 5
	v_readlane_b32 s62, v251, 6
	v_readlane_b32 s63, v251, 7
	s_branch .LBB0_830
